# 64-row-per-wave attention: staging moved after QK MFMAs, early V reads, waves 4-7 barrier between the two blocks' softmax (half-tile stagger)
# speedup vs baseline: 1.0472x; 1.0337x over previous
; __device__ __forceinline__ void qkt(f32x16& p0, f32x16& p1, const char* Ks, const bf16x8* qr, int r32, int hi) {
;     p0 = f32x16{}; p1 = f32x16{};
; #pragma unroll
;     for (int d0 = 0; d0 < 6; ++d0) { const int cb = (d0 * 16 + hi * 8) * 2;
;         bf16x8 b0 = *reinterpret_cast<const bf16x8*>(Ks + KSWZ(r32, cb));
;         bf16x8 b1 = *reinterpret_cast<const bf16x8*>(Ks + KSWZ(32 + r32, cb));
;         p0 = __builtin_amdgcn_mfma_f32_32x32x16_bf16(b0, qr[d0], p0, 0, 0, 0);
;         p1 = __builtin_amdgcn_mfma_f32_32x32x16_bf16(b1, qr[d0], p1, 0, 0, 0); }
; }
.LA_loop:
	v_add_u32_e32 v247, s18, v236
	ds_read_b128 v[212:215], v247 offset:49152
	ds_read_b128 v[216:219], v247 offset:57344
	v_add_u32_e32 v247, s18, v237
	ds_read_b128 v[220:223], v247 offset:49152
	ds_read_b128 v[224:227], v247 offset:57344
	s_waitcnt lgkmcnt(2)
	v_mfma_f32_32x32x16_bf16 v[66:81], v[212:215], v[142:145], 0
	v_mfma_f32_32x32x16_bf16 v[82:97], v[216:219], v[142:145], 0
	v_mfma_f32_32x32x16_bf16 v[98:113], v[212:215], v[166:169], 0
	v_mfma_f32_32x32x16_bf16 v[114:129], v[216:219], v[166:169], 0
	v_add_u32_e32 v247, s18, v238
	ds_read_b128 v[212:215], v247 offset:49152
	ds_read_b128 v[216:219], v247 offset:57344
	s_waitcnt lgkmcnt(2)
	v_mfma_f32_32x32x16_bf16 v[66:81], v[220:223], v[146:149], v[66:81]
	v_mfma_f32_32x32x16_bf16 v[82:97], v[224:227], v[146:149], v[82:97]
	v_mfma_f32_32x32x16_bf16 v[98:113], v[220:223], v[170:173], v[98:113]
	v_mfma_f32_32x32x16_bf16 v[114:129], v[224:227], v[170:173], v[114:129]
	v_add_u32_e32 v247, s18, v239
	ds_read_b128 v[220:223], v247 offset:49152
	ds_read_b128 v[224:227], v247 offset:57344
	s_waitcnt lgkmcnt(2)
	v_mfma_f32_32x32x16_bf16 v[66:81], v[212:215], v[150:153], v[66:81]
	v_mfma_f32_32x32x16_bf16 v[82:97], v[216:219], v[150:153], v[82:97]
	v_mfma_f32_32x32x16_bf16 v[98:113], v[212:215], v[174:177], v[98:113]
	v_mfma_f32_32x32x16_bf16 v[114:129], v[216:219], v[174:177], v[114:129]
	v_add_u32_e32 v247, s18, v236
	ds_read_b128 v[212:215], v247 offset:49280
	ds_read_b128 v[216:219], v247 offset:57472
	s_waitcnt lgkmcnt(2)
	v_mfma_f32_32x32x16_bf16 v[66:81], v[220:223], v[154:157], v[66:81]
	v_mfma_f32_32x32x16_bf16 v[82:97], v[224:227], v[154:157], v[82:97]
	v_mfma_f32_32x32x16_bf16 v[98:113], v[220:223], v[178:181], v[98:113]
	v_mfma_f32_32x32x16_bf16 v[114:129], v[224:227], v[178:181], v[114:129]
	v_add_u32_e32 v247, s18, v237
	ds_read_b128 v[220:223], v247 offset:49280
	ds_read_b128 v[224:227], v247 offset:57472
	s_waitcnt lgkmcnt(2)
	v_mfma_f32_32x32x16_bf16 v[66:81], v[212:215], v[158:161], v[66:81]
	v_mfma_f32_32x32x16_bf16 v[82:97], v[216:219], v[158:161], v[82:97]
	v_mfma_f32_32x32x16_bf16 v[98:113], v[212:215], v[182:185], v[98:113]
	v_mfma_f32_32x32x16_bf16 v[114:129], v[216:219], v[182:185], v[114:129]
	s_waitcnt lgkmcnt(0)
	v_mfma_f32_32x32x16_bf16 v[66:81], v[220:223], v[162:165], v[66:81]
	v_mfma_f32_32x32x16_bf16 v[82:97], v[224:227], v[162:165], v[82:97]
	v_mfma_f32_32x32x16_bf16 v[98:113], v[220:223], v[186:189], v[98:113]
	v_mfma_f32_32x32x16_bf16 v[114:129], v[224:227], v[186:189], v[114:129]
	s_cmp_gt_u32 s16, 62
	s_cbranch_scc1 .LA_nosw
	s_waitcnt vmcnt(0)
	v_add_u32_e32 v246, s19, v240
	v_add_u32_e32 v245, s19, v241
	ds_write_b128 v246, v[228:231]
	ds_write_b128 v245, v[130:133]
	s_cmp_eq_u64 s[2:3], 0
	s_cbranch_scc1 .LA_swl
	v_add_u32_e32 v245, s19, v242
	ds_write_b128 v245, v[248:251] offset:49152

; __device__ __forceinline__ void partialSM(f32x16& p0, f32x16& p1, float& m_reg, float& mn, float& alpha) {
;     constexpr float Cc = SCALE * 1.4426950408889634f;
;     float pmax = p0[0];
; #pragma unroll
;     for (int r = 1; r < 16; ++r) pmax = fmaxf(pmax, p0[r]);
; #pragma unroll
;     for (int r = 0; r < 16; ++r) pmax = fmaxf(pmax, p1[r]);
;     { auto rr = __builtin_amdgcn_permlane32_swap(__float_as_uint(pmax), __float_as_uint(pmax), false, false);
;       pmax = fmaxf(__uint_as_float(rr[0]), __uint_as_float(rr[1])); }
;     if (__builtin_expect(__all(pmax - m_reg <= THR / SCALE), 1)) { mn = m_reg; alpha = 1.f; }
;     else { mn = fmaxf(m_reg, pmax); alpha = __builtin_amdgcn_exp2f((m_reg - mn) * Cc); m_reg = mn; }
;     const float mnC = -mn * Cc;
;     { typedef float f32x2 __attribute__((ext_vector_type(2))); const f32x2 c2 = {Cc, Cc}, m2 = {mnC, mnC};
; #pragma unroll
;       for (int r = 0; r < 16; r += 2) { f32x2 t = {p0[r], p0[r + 1]}; t = __builtin_elementwise_fma(t, c2, m2); p0[r] = t.x; p0[r + 1] = t.y; }
; #pragma unroll
;       for (int r = 0; r < 16; r += 2) { f32x2 t = {p1[r], p1[r + 1]}; t = __builtin_elementwise_fma(t, c2, m2); p1[r] = t.x; p1[r + 1] = t.y; } }
; #pragma unroll
;     for (int r = 0; r < 16; ++r) p0[r] = __builtin_amdgcn_exp2f(p0[r]);
; }
; __device__ __forceinline__ void finishSM(f32x16& p0, f32x16& p1, float alpha, float& l_reg, bf16x8& pa0, bf16x8& pa1, bf16x8& pa2, bf16x8& pa3) {
; #pragma unroll
;     for (int r = 0; r < 16; ++r) p1[r] = __builtin_amdgcn_exp2f(p1[r]);
;     float ps;
;     { typedef float f32x2 __attribute__((ext_vector_type(2))); f32x2 s0 = {p0[0], p0[1]}, s1 = {p1[0], p1[1]};
; #pragma unroll
;       for (int r = 2; r < 16; r += 2) { s0 += (f32x2){p0[r], p0[r + 1]}; s1 += (f32x2){p1[r], p1[r + 1]}; }
;       s0 += s1; ps = s0.x + s0.y; }
;     { auto rr = __builtin_amdgcn_permlane32_swap(__float_as_uint(ps), __float_as_uint(ps), false, false);
;       ps = __uint_as_float(rr[0]) + __uint_as_float(rr[1]); }
;     l_reg = l_reg * alpha + ps;
;     ...
;     PK4(p0, 0, pa0); PK4(p0, 8, pa1); PK4(p1, 0, pa2); PK4(p1, 8, pa3);
;     ...
; }
.LA_nosw:
	v_add_u32_e32 v202, s18, v235
	v_max_f32_e32 v212, v66, v67
	v_max_f32_e32 v213, v82, v83
	v_max3_f32 v212, v212, v68, v69
	v_max3_f32 v213, v213, v84, v85
	v_max3_f32 v212, v212, v70, v71
	v_max3_f32 v213, v213, v86, v87
	v_max3_f32 v212, v212, v72, v73
	v_max3_f32 v213, v213, v88, v89
	v_max3_f32 v212, v212, v74, v75
	v_max3_f32 v213, v213, v90, v91
	v_max3_f32 v212, v212, v76, v77
	v_max3_f32 v213, v213, v92, v93
	v_max3_f32 v212, v212, v78, v79
	v_max3_f32 v213, v213, v94, v95
	v_max3_f32 v212, v212, v80, v81
	v_max3_f32 v213, v213, v96, v97
	v_max_f32_e32 v212, v212, v213
	v_mov_b32_e32 v213, v212
	s_nop 1
	v_permlane32_swap_b32_e32 v212, v213
	v_max_f32_e32 v212, v212, v213
	v_sub_f32_e32 v214, v212, v141
	v_cmp_ge_f32_e32 vcc, s67, v214
	v_max_f32_e32 v212, v141, v212
	v_sub_f32_e32 v214, v141, v212
	v_mul_f32_e32 v214, 0x3e16c740, v214
	v_exp_f32_e32 v215, v214
	s_cmp_eq_u64 vcc, exec
	s_cselect_b64 s[58:59], -1, 0
	v_cndmask_b32_e64 v141, v212, v141, s[58:59]
	v_cndmask_b32_e64 v215, v215, 1.0, s[58:59]
	v_mul_f32_e32 v216, 0xbe16c740, v141
	v_fma_f32 v66, v66, s52, v216
	v_fma_f32 v67, v67, s52, v216
	v_fma_f32 v68, v68, s52, v216
	v_fma_f32 v69, v69, s52, v216
	v_fma_f32 v70, v70, s52, v216
	v_fma_f32 v71, v71, s52, v216
	v_fma_f32 v72, v72, s52, v216
	v_fma_f32 v73, v73, s52, v216
	v_fma_f32 v74, v74, s52, v216
	v_fma_f32 v75, v75, s52, v216
	v_fma_f32 v76, v76, s52, v216
	v_fma_f32 v77, v77, s52, v216
	v_fma_f32 v78, v78, s52, v216
	v_fma_f32 v79, v79, s52, v216
	v_fma_f32 v80, v80, s52, v216
	v_fma_f32 v81, v81, s52, v216
	v_fma_f32 v82, v82, s52, v216
	v_fma_f32 v83, v83, s52, v216
	v_fma_f32 v84, v84, s52, v216
	v_fma_f32 v85, v85, s52, v216
	v_fma_f32 v86, v86, s52, v216
	v_fma_f32 v87, v87, s52, v216
	v_fma_f32 v88, v88, s52, v216
	v_fma_f32 v89, v89, s52, v216
	v_fma_f32 v90, v90, s52, v216
	v_fma_f32 v91, v91, s52, v216
	v_fma_f32 v92, v92, s52, v216
	v_fma_f32 v93, v93, s52, v216
	v_fma_f32 v94, v94, s52, v216
	v_fma_f32 v95, v95, s52, v216
	v_fma_f32 v96, v96, s52, v216
	v_fma_f32 v97, v97, s52, v216
	v_exp_f32_e32 v66, v66
	v_exp_f32_e32 v67, v67
	v_exp_f32_e32 v68, v68
	v_exp_f32_e32 v69, v69
	v_exp_f32_e32 v70, v70
	v_exp_f32_e32 v71, v71
	v_exp_f32_e32 v72, v72
	v_exp_f32_e32 v73, v73
	v_exp_f32_e32 v74, v74
	v_exp_f32_e32 v75, v75
	v_exp_f32_e32 v76, v76
	v_exp_f32_e32 v77, v77
	v_exp_f32_e32 v78, v78
	v_exp_f32_e32 v79, v79
	v_exp_f32_e32 v80, v80
	v_exp_f32_e32 v81, v81
	v_exp_f32_e32 v82, v82
	v_exp_f32_e32 v83, v83
	v_exp_f32_e32 v84, v84
	v_exp_f32_e32 v85, v85
	v_exp_f32_e32 v86, v86
	v_exp_f32_e32 v87, v87
	v_exp_f32_e32 v88, v88
	v_exp_f32_e32 v89, v89
	v_exp_f32_e32 v90, v90
	v_exp_f32_e32 v91, v91
	v_exp_f32_e32 v92, v92
	v_exp_f32_e32 v93, v93
	v_exp_f32_e32 v94, v94
	v_exp_f32_e32 v95, v95
	v_exp_f32_e32 v96, v96
	v_exp_f32_e32 v97, v97
	v_add_f32_e32 v212, v66, v68
	v_add_f32_e32 v213, v67, v69
	v_add_f32_e32 v212, v70, v212
	v_add_f32_e32 v213, v71, v213
	v_add_f32_e32 v212, v72, v212
	v_add_f32_e32 v213, v73, v213
	v_add_f32_e32 v212, v74, v212
	v_add_f32_e32 v213, v75, v213
	v_add_f32_e32 v212, v76, v212
	v_add_f32_e32 v213, v77, v213
	v_add_f32_e32 v212, v78, v212
	v_add_f32_e32 v213, v79, v213
	v_add_f32_e32 v212, v80, v212
	v_add_f32_e32 v213, v81, v213
	v_add_f32_e32 v212, v82, v212
	v_add_f32_e32 v213, v83, v213
	v_add_f32_e32 v212, v84, v212
	v_add_f32_e32 v213, v85, v213
	v_add_f32_e32 v212, v86, v212
	v_add_f32_e32 v213, v87, v213
	v_add_f32_e32 v212, v88, v212
	v_add_f32_e32 v213, v89, v213
	v_add_f32_e32 v212, v90, v212
	v_add_f32_e32 v213, v91, v213
	v_add_f32_e32 v212, v92, v212
	v_add_f32_e32 v213, v93, v213
	v_add_f32_e32 v212, v94, v212
	v_add_f32_e32 v213, v95, v213
	v_add_f32_e32 v212, v96, v212
	v_add_f32_e32 v213, v97, v213
	v_add_f32_e32 v212, v212, v213
	v_fma_f32 v254, v254, v215, v212
	v_cvt_pk_bf16_f32 v66, v66, v67
	v_cvt_pk_bf16_f32 v67, v68, v69
	v_cvt_pk_bf16_f32 v68, v70, v71
	v_cvt_pk_bf16_f32 v69, v72, v73
	v_cvt_pk_bf16_f32 v70, v74, v75
	v_cvt_pk_bf16_f32 v71, v76, v77
	v_cvt_pk_bf16_f32 v72, v78, v79
	v_cvt_pk_bf16_f32 v73, v80, v81
	v_cvt_pk_bf16_f32 v82, v82, v83
	v_cvt_pk_bf16_f32 v83, v84, v85
	v_cvt_pk_bf16_f32 v84, v86, v87
	v_cvt_pk_bf16_f32 v85, v88, v89
	v_cvt_pk_bf16_f32 v86, v90, v91
	v_cvt_pk_bf16_f32 v87, v92, v93
	v_cvt_pk_bf16_f32 v88, v94, v95
	v_cvt_pk_bf16_f32 v89, v96, v97
	v_permlane32_swap_b32_e32 v66, v68
	v_permlane32_swap_b32_e32 v67, v69
	v_permlane32_swap_b32_e32 v70, v72
	v_permlane32_swap_b32_e32 v71, v73
	v_permlane32_swap_b32_e32 v82, v84
	v_permlane32_swap_b32_e32 v83, v85
	v_permlane32_swap_b32_e32 v86, v88
	v_permlane32_swap_b32_e32 v87, v89
	v_cmp_gt_f32_e32 vcc, 1.0, v215
	s_cbranch_vccz .LA_rs0
	s_and_saveexec_b64 s[60:61], s[4:5]
	ds_write_b32 v234, v215 offset:128
	s_or_b64 exec, exec, s[60:61]
	s_waitcnt lgkmcnt(0)
	v_add_u32_e32 v245, v232, v233
	ds_read_b128 v[220:223], v245 offset:224
	ds_read_b128 v[224:227], v245 offset:192
	ds_read_b128 v[216:219], v245 offset:160
	ds_read_b128 v[212:215], v245 offset:128
	s_waitcnt lgkmcnt(0)
	v_mul_f32_e32 v12, v12, v220
	v_mul_f32_e32 v13, v13, v221
	v_mul_f32_e32 v14, v14, v222
	v_mul_f32_e32 v15, v15, v223
	v_mul_f32_e32 v8, v8, v224
	v_mul_f32_e32 v9, v9, v225
	v_mul_f32_e32 v10, v10, v226
	v_mul_f32_e32 v11, v11, v227
	v_mul_f32_e32 v4, v4, v216
	v_mul_f32_e32 v5, v5, v217
	v_mul_f32_e32 v6, v6, v218
	v_mul_f32_e32 v7, v7, v219
	v_mul_f32_e32 v0, v0, v212
	v_mul_f32_e32 v1, v1, v213
	v_mul_f32_e32 v2, v2, v214
	v_mul_f32_e32 v3, v3, v215
	v_mul_f32_e32 v28, v28, v220
	v_mul_f32_e32 v29, v29, v221
	v_mul_f32_e32 v30, v30, v222
	v_mul_f32_e32 v31, v31, v223
	v_mul_f32_e32 v24, v24, v224
	v_mul_f32_e32 v25, v25, v225
	v_mul_f32_e32 v26, v26, v226
	v_mul_f32_e32 v27, v27, v227
	v_mul_f32_e32 v20, v20, v216
	v_mul_f32_e32 v21, v21, v217
	v_mul_f32_e32 v22, v22, v218
	v_mul_f32_e32 v23, v23, v219
	v_mul_f32_e32 v16, v16, v212
	v_mul_f32_e32 v17, v17, v213
	v_mul_f32_e32 v18, v18, v214
	v_mul_f32_e32 v19, v19, v215
; __device__ __forceinline__ void partialSM(f32x16& p0, f32x16& p1, float& m_reg, float& mn, float& alpha) {
;     constexpr float Cc = SCALE * 1.4426950408889634f;
;     float pmax = p0[0];
; #pragma unroll
;     for (int r = 1; r < 16; ++r) pmax = fmaxf(pmax, p0[r]);
; #pragma unroll
;     for (int r = 0; r < 16; ++r) pmax = fmaxf(pmax, p1[r]);
;     { auto rr = __builtin_amdgcn_permlane32_swap(__float_as_uint(pmax), __float_as_uint(pmax), false, false);
;       pmax = fmaxf(__uint_as_float(rr[0]), __uint_as_float(rr[1])); }
;     if (__builtin_expect(__all(pmax - m_reg <= THR / SCALE), 1)) { mn = m_reg; alpha = 1.f; }
;     else { mn = fmaxf(m_reg, pmax); alpha = __builtin_amdgcn_exp2f((m_reg - mn) * Cc); m_reg = mn; }
;     const float mnC = -mn * Cc;
;     { typedef float f32x2 __attribute__((ext_vector_type(2))); const f32x2 c2 = {Cc, Cc}, m2 = {mnC, mnC};
; #pragma unroll
;       for (int r = 0; r < 16; r += 2) { f32x2 t = {p0[r], p0[r + 1]}; t = __builtin_elementwise_fma(t, c2, m2); p0[r] = t.x; p0[r + 1] = t.y; }
; #pragma unroll
;       for (int r = 0; r < 16; r += 2) { f32x2 t = {p1[r], p1[r + 1]}; t = __builtin_elementwise_fma(t, c2, m2); p1[r] = t.x; p1[r + 1] = t.y; } }
; #pragma unroll
;     for (int r = 0; r < 16; ++r) p0[r] = __builtin_amdgcn_exp2f(p0[r]);
; }
; __device__ __forceinline__ void finishSM(f32x16& p0, f32x16& p1, float alpha, float& l_reg, bf16x8& pa0, bf16x8& pa1, bf16x8& pa2, bf16x8& pa3) {
; #pragma unroll
;     for (int r = 0; r < 16; ++r) p1[r] = __builtin_amdgcn_exp2f(p1[r]);
;     float ps;
;     { typedef float f32x2 __attribute__((ext_vector_type(2))); f32x2 s0 = {p0[0], p0[1]}, s1 = {p1[0], p1[1]};
; #pragma unroll
;       for (int r = 2; r < 16; r += 2) { s0 += (f32x2){p0[r], p0[r + 1]}; s1 += (f32x2){p1[r], p1[r + 1]}; }
;       s0 += s1; ps = s0.x + s0.y; }
;     { auto rr = __builtin_amdgcn_permlane32_swap(__float_as_uint(ps), __float_as_uint(ps), false, false);
;       ps = __uint_as_float(rr[0]) + __uint_as_float(rr[1]); }
;     l_reg = l_reg * alpha + ps;
;     ...
;     PK4(p0, 0, pa0); PK4(p0, 8, pa1); PK4(p1, 0, pa2); PK4(p1, 8, pa3);
;     ...
; }
; template <int D0> __device__ __forceinline__ void pv_one(f32x16& od, int vb, bf16x8 pa0, bf16x8 pa1, bf16x8 pa2, bf16x8 pa3) {
.LA_rs0:
	s_waitcnt lgkmcnt(0)
	s_cmp_eq_u64 s[2:3], 0
	s_cbranch_scc0 .LA_g1b
	s_barrier
.LA_g1b:
	ds_read_b64_tr_b16 v[74:75], v202 offset:0
	ds_read_b64_tr_b16 v[76:77], v202 offset:2048
	ds_read_b64_tr_b16 v[78:79], v202 offset:4096
	ds_read_b64_tr_b16 v[80:81], v202 offset:6144
	ds_read_b64_tr_b16 v[90:91], v202 offset:8192
	ds_read_b64_tr_b16 v[92:93], v202 offset:10240
	ds_read_b64_tr_b16 v[94:95], v202 offset:12288
	ds_read_b64_tr_b16 v[96:97], v202 offset:14336
	v_max_f32_e32 v212, v98, v99
	v_max_f32_e32 v213, v114, v115
	v_max3_f32 v212, v212, v100, v101
	v_max3_f32 v213, v213, v116, v117
	v_max3_f32 v212, v212, v102, v103
	v_max3_f32 v213, v213, v118, v119
	v_max3_f32 v212, v212, v104, v105
	v_max3_f32 v213, v213, v120, v121
	v_max3_f32 v212, v212, v106, v107
	v_max3_f32 v213, v213, v122, v123
	v_max3_f32 v212, v212, v108, v109
	v_max3_f32 v213, v213, v124, v125
	v_max3_f32 v212, v212, v110, v111
	v_max3_f32 v213, v213, v126, v127
	v_max3_f32 v212, v212, v112, v113
	v_max3_f32 v213, v213, v128, v129
	v_max_f32_e32 v212, v212, v213
	v_mov_b32_e32 v213, v212
	s_nop 1
	v_permlane32_swap_b32_e32 v212, v213
	v_max_f32_e32 v212, v212, v213
	v_sub_f32_e32 v214, v212, v139
	v_cmp_ge_f32_e32 vcc, s67, v214
	v_max_f32_e32 v212, v139, v212
	v_sub_f32_e32 v214, v139, v212
	v_mul_f32_e32 v214, 0x3e16c740, v214
	v_exp_f32_e32 v215, v214
	s_cmp_eq_u64 vcc, exec
	s_cselect_b64 s[58:59], -1, 0
	v_cndmask_b32_e64 v139, v212, v139, s[58:59]
	v_cndmask_b32_e64 v215, v215, 1.0, s[58:59]
	v_mul_f32_e32 v216, 0xbe16c740, v139
	v_fma_f32 v98, v98, s52, v216
	v_fma_f32 v99, v99, s52, v216
	v_fma_f32 v100, v100, s52, v216
	v_fma_f32 v101, v101, s52, v216
	v_fma_f32 v102, v102, s52, v216
	v_fma_f32 v103, v103, s52, v216
	v_fma_f32 v104, v104, s52, v216
	v_fma_f32 v105, v105, s52, v216
	v_fma_f32 v106, v106, s52, v216
	v_fma_f32 v107, v107, s52, v216
	v_fma_f32 v108, v108, s52, v216
	v_fma_f32 v109, v109, s52, v216
	v_fma_f32 v110, v110, s52, v216
	v_fma_f32 v111, v111, s52, v216
	v_fma_f32 v112, v112, s52, v216
	v_fma_f32 v113, v113, s52, v216
	v_fma_f32 v114, v114, s52, v216
	v_fma_f32 v115, v115, s52, v216
	v_fma_f32 v116, v116, s52, v216
	v_fma_f32 v117, v117, s52, v216
	v_fma_f32 v118, v118, s52, v216
	v_fma_f32 v119, v119, s52, v216
	v_fma_f32 v120, v120, s52, v216
	v_fma_f32 v121, v121, s52, v216
	v_fma_f32 v122, v122, s52, v216
	v_fma_f32 v123, v123, s52, v216
	v_fma_f32 v124, v124, s52, v216
	v_fma_f32 v125, v125, s52, v216
	v_fma_f32 v126, v126, s52, v216
	v_fma_f32 v127, v127, s52, v216
	v_fma_f32 v128, v128, s52, v216
	v_fma_f32 v129, v129, s52, v216
	v_exp_f32_e32 v98, v98
	v_exp_f32_e32 v99, v99
	v_exp_f32_e32 v100, v100
	v_exp_f32_e32 v101, v101
	v_exp_f32_e32 v102, v102
	v_exp_f32_e32 v103, v103
	v_exp_f32_e32 v104, v104
	v_exp_f32_e32 v105, v105
	v_exp_f32_e32 v106, v106
	v_exp_f32_e32 v107, v107
	v_exp_f32_e32 v108, v108
	v_exp_f32_e32 v109, v109
	v_exp_f32_e32 v110, v110
	v_exp_f32_e32 v111, v111
	v_exp_f32_e32 v112, v112
	v_exp_f32_e32 v113, v113
	v_exp_f32_e32 v114, v114
	v_exp_f32_e32 v115, v115
	v_exp_f32_e32 v116, v116
	v_exp_f32_e32 v117, v117
	v_exp_f32_e32 v118, v118
	v_exp_f32_e32 v119, v119
	v_exp_f32_e32 v120, v120
	v_exp_f32_e32 v121, v121
	v_exp_f32_e32 v122, v122
	v_exp_f32_e32 v123, v123
	v_exp_f32_e32 v124, v124
	v_exp_f32_e32 v125, v125
	v_exp_f32_e32 v126, v126
	v_exp_f32_e32 v127, v127
	v_exp_f32_e32 v128, v128
	v_exp_f32_e32 v129, v129
	v_add_f32_e32 v212, v98, v100
	v_add_f32_e32 v213, v99, v101
	v_add_f32_e32 v212, v102, v212
	v_add_f32_e32 v213, v103, v213
	v_add_f32_e32 v212, v104, v212
	v_add_f32_e32 v213, v105, v213
	v_add_f32_e32 v212, v106, v212
	v_add_f32_e32 v213, v107, v213
	v_add_f32_e32 v212, v108, v212
	v_add_f32_e32 v213, v109, v213
	v_add_f32_e32 v212, v110, v212
	v_add_f32_e32 v213, v111, v213
	v_add_f32_e32 v212, v112, v212
	v_add_f32_e32 v213, v113, v213
	v_add_f32_e32 v212, v114, v212
	v_add_f32_e32 v213, v115, v213
	v_add_f32_e32 v212, v116, v212
	v_add_f32_e32 v213, v117, v213
	v_add_f32_e32 v212, v118, v212
	v_add_f32_e32 v213, v119, v213
	v_add_f32_e32 v212, v120, v212
	v_add_f32_e32 v213, v121, v213
	v_add_f32_e32 v212, v122, v212
	v_add_f32_e32 v213, v123, v213
	v_add_f32_e32 v212, v124, v212
	v_add_f32_e32 v213, v125, v213
	v_add_f32_e32 v212, v126, v212
	v_add_f32_e32 v213, v127, v213
	v_add_f32_e32 v212, v128, v212
	v_add_f32_e32 v213, v129, v213
	v_add_f32_e32 v212, v212, v213
	v_fma_f32 v255, v255, v215, v212
	v_cvt_pk_bf16_f32 v98, v98, v99
	v_cvt_pk_bf16_f32 v99, v100, v101
	v_cvt_pk_bf16_f32 v100, v102, v103
	v_cvt_pk_bf16_f32 v101, v104, v105
	v_cvt_pk_bf16_f32 v102, v106, v107
	v_cvt_pk_bf16_f32 v103, v108, v109
	v_cvt_pk_bf16_f32 v104, v110, v111
	v_cvt_pk_bf16_f32 v105, v112, v113
	v_cvt_pk_bf16_f32 v114, v114, v115
	v_cvt_pk_bf16_f32 v115, v116, v117
	v_cvt_pk_bf16_f32 v116, v118, v119
	v_cvt_pk_bf16_f32 v117, v120, v121
	v_cvt_pk_bf16_f32 v118, v122, v123
	v_cvt_pk_bf16_f32 v119, v124, v125
	v_cvt_pk_bf16_f32 v120, v126, v127
	v_cvt_pk_bf16_f32 v121, v128, v129
	v_permlane32_swap_b32_e32 v98, v100
	v_permlane32_swap_b32_e32 v99, v101
	v_permlane32_swap_b32_e32 v102, v104
	v_permlane32_swap_b32_e32 v103, v105
	v_permlane32_swap_b32_e32 v114, v116
	v_permlane32_swap_b32_e32 v115, v117
	v_permlane32_swap_b32_e32 v118, v120
	v_permlane32_swap_b32_e32 v119, v121
	v_cmp_gt_f32_e32 vcc, 1.0, v215
	s_cbranch_vccz .LA_rs1
	s_and_saveexec_b64 s[60:61], s[4:5]
	ds_write_b32 v234, v215 offset:128
	s_or_b64 exec, exec, s[60:61]
	s_waitcnt lgkmcnt(0)
	v_add_u32_e32 v245, v232, v233
	ds_read_b128 v[220:223], v245 offset:224
	ds_read_b128 v[224:227], v245 offset:192
	ds_read_b128 v[216:219], v245 offset:160
	ds_read_b128 v[212:215], v245 offset:128
	s_waitcnt lgkmcnt(0)
	v_mul_f32_e32 v44, v44, v220
	v_mul_f32_e32 v45, v45, v221
	v_mul_f32_e32 v46, v46, v222
	v_mul_f32_e32 v47, v47, v223
	v_mul_f32_e32 v40, v40, v224
	v_mul_f32_e32 v41, v41, v225
	v_mul_f32_e32 v42, v42, v226
	v_mul_f32_e32 v43, v43, v227
	v_mul_f32_e32 v36, v36, v216
	v_mul_f32_e32 v37, v37, v217
	v_mul_f32_e32 v38, v38, v218
	v_mul_f32_e32 v39, v39, v219
	v_mul_f32_e32 v32, v32, v212
	v_mul_f32_e32 v33, v33, v213
	v_mul_f32_e32 v34, v34, v214
	v_mul_f32_e32 v35, v35, v215
	v_mul_f32_e32 v60, v60, v220
	v_mul_f32_e32 v61, v61, v221
	v_mul_f32_e32 v62, v62, v222
	v_mul_f32_e32 v63, v63, v223
	v_mul_f32_e32 v56, v56, v224
	v_mul_f32_e32 v57, v57, v225
	v_mul_f32_e32 v58, v58, v226
	v_mul_f32_e32 v59, v59, v227
	v_mul_f32_e32 v52, v52, v216
	v_mul_f32_e32 v53, v53, v217
	v_mul_f32_e32 v54, v54, v218
	v_mul_f32_e32 v55, v55, v219
	v_mul_f32_e32 v48, v48, v212
	v_mul_f32_e32 v49, v49, v213
	v_mul_f32_e32 v50, v50, v214
	v_mul_f32_e32 v51, v51, v215
; #define SBAR() __builtin_amdgcn_sched_barrier(0)
; #define SWAIT() asm volatile("s_waitcnt vmcnt(3)" ::: "memory")
; template <int D0> __device__ __forceinline__ void pv_one(f32x16& od, int vb, bf16x8 pa0, bf16x8 pa1, bf16x8 pa2, bf16x8 pa3) {
;     const s16x4 l0 = tr_read<v_rd_off(D0, 0, 0)>(vb), h0 = tr_read<v_rd_off(D0, 0, 1)>(vb), l1 = tr_read<v_rd_off(D0, 1, 0)>(vb), h1 = tr_read<v_rd_off(D0, 1, 1)>(vb);
;     const s16x4 l2 = tr_read<v_rd_off(D0, 2, 0)>(vb), h2 = tr_read<v_rd_off(D0, 2, 1)>(vb), l3 = tr_read<v_rd_off(D0, 3, 0)>(vb), h3 = tr_read<v_rd_off(D0, 3, 1)>(vb);
;     asm volatile("s_waitcnt lgkmcnt(0)" ::: "memory"); SBAR();
;     ...
;     od = __builtin_amdgcn_mfma_f32_32x32x16_bf16(pa0, PK(l0, h0), od, 0, 0, 0);
;     od = __builtin_amdgcn_mfma_f32_32x32x16_bf16(pa1, PK(l1, h1), od, 0, 0, 0);
;     od = __builtin_amdgcn_mfma_f32_32x32x16_bf16(pa2, PK(l2, h2), od, 0, 0, 0);
;     od = __builtin_amdgcn_mfma_f32_32x32x16_bf16(pa3, PK(l3, h3), od, 0, 0, 0);
;     ...
; }
; __device__ __forceinline__ void attn_body(const bf16_t* __restrict__ Qb, const bf16_t* __restrict__ KVh, const bf16_t* __restrict__ KR, const float* __restrict__ ropeq,
;                                           bf16_t* __restrict__ Ob, int seq, char* lds, const int tid) {
;     ...
;     for (int j = 1; j + 1 < NT; j += 2) {
;         SBAR(); qkt(pB0, pB1, K_lds + bc * SHM_K, qr, r32, hi);
;         finishSM(pA0, pA1, alA, l_reg, pa0, pa1, pa2, pa3); SBAR();
;         SLOAD(SO, (j + 2) * KVBLK); SBAR();
;         pv_d0(o, vb0 + bp * (int)SHM_V, pa0, pa1, pa2, pa3); partialSM(pB0, pB1, m_reg, mnB, alB);
;         SWAIT(); SWRITE(bn, SE);
;         RESC(alB); __syncthreads();
;         { const int t = bp; bp = bc; bc = bn; bn = t; }
;         SBAR(); qkt(pA0, pA1, K_lds + bc * SHM_K, qr, r32, hi);
;         finishSM(pB0, pB1, alB, l_reg, pa0, pa1, pa2, pa3); SBAR();
;         if (j + 3 < NT) SLOAD(SE, (j + 3) * KVBLK); SBAR();
;         pv_d0(o, vb0 + bp * (int)SHM_V, pa0, pa1, pa2, pa3); partialSM(pA0, pA1, m_reg, mnA, alA);
;         SWAIT(); SWRITE(bn, SO);
;         RESC(alA); __syncthreads();
;         { const int t = bp; bp = bc; bc = bn; bn = t; }
;     }
.LA_rs1:
	ds_read_b64_tr_b16 v[106:107], v202 offset:512
	ds_read_b64_tr_b16 v[108:109], v202 offset:2560
	ds_read_b64_tr_b16 v[110:111], v202 offset:4608
	ds_read_b64_tr_b16 v[112:113], v202 offset:6656
	ds_read_b64_tr_b16 v[122:123], v202 offset:8704
	ds_read_b64_tr_b16 v[124:125], v202 offset:10752
	ds_read_b64_tr_b16 v[126:127], v202 offset:12800
	ds_read_b64_tr_b16 v[128:129], v202 offset:14848
	v_mfma_f32_32x32x16_bf16 v[0:15], v[66:69], v[74:77], v[0:15]
	v_mfma_f32_32x32x16_bf16 v[32:47], v[98:101], v[74:77], v[32:47]
	v_mfma_f32_32x32x16_bf16 v[0:15], v[70:73], v[78:81], v[0:15]
	v_mfma_f32_32x32x16_bf16 v[32:47], v[102:105], v[78:81], v[32:47]
	v_mfma_f32_32x32x16_bf16 v[0:15], v[82:85], v[90:93], v[0:15]
	v_mfma_f32_32x32x16_bf16 v[32:47], v[114:117], v[90:93], v[32:47]
	v_mfma_f32_32x32x16_bf16 v[0:15], v[86:89], v[94:97], v[0:15]
	v_mfma_f32_32x32x16_bf16 v[32:47], v[118:121], v[94:97], v[32:47]
	s_waitcnt lgkmcnt(6)
	v_mfma_f32_32x32x16_bf16 v[16:31], v[66:69], v[106:109], v[16:31]
	v_mfma_f32_32x32x16_bf16 v[48:63], v[98:101], v[106:109], v[48:63]
	s_waitcnt lgkmcnt(4)
	v_mfma_f32_32x32x16_bf16 v[16:31], v[70:73], v[110:113], v[16:31]
	v_mfma_f32_32x32x16_bf16 v[48:63], v[102:105], v[110:113], v[48:63]
	s_waitcnt lgkmcnt(2)
	v_mfma_f32_32x32x16_bf16 v[16:31], v[82:85], v[122:125], v[16:31]
	v_mfma_f32_32x32x16_bf16 v[48:63], v[114:117], v[122:125], v[48:63]
	s_waitcnt lgkmcnt(0)
	v_mfma_f32_32x32x16_bf16 v[16:31], v[86:89], v[126:129], v[16:31]
	v_mfma_f32_32x32x16_bf16 v[48:63], v[118:121], v[126:129], v[48:63]
	s_waitcnt lgkmcnt(0)
	s_cmp_eq_u64 s[2:3], 0
	s_cbranch_scc1 .LA_g0b
	s_barrier
.LA_g0b:
	s_add_i32 s16, s16, 1
	s_mov_b32 s17, s18
	s_mov_b32 s18, s19
	s_mov_b32 s19, s22
	s_mov_b32 s22, s17
	s_cmp_lt_u32 s16, 64
	s_cbranch_scc1 .LA_loop
	v_and_b32_e32 v245, 31, v211
	v_lshrrev_b32_e32 v246, 5, v211
	v_lshlrev_b32_e32 v202, 1, v245
	v_lshl_add_u32 v202, v246, 13, v202
	v_mov_b32_e32 v203, v254
	s_nop 1
	v_permlane32_swap_b32_e32 v254, v203
	v_add_f32_e32 v254, v254, v203
	s_and_saveexec_b64 s[60:61], s[4:5]
	ds_write_b32 v234, v254
	s_or_b64 exec, exec, s[60:61]
	s_waitcnt lgkmcnt(0)
	v_add_u32_e32 v245, v232, v233
	ds_read_b128 v[212:215], v245 offset:0
	ds_read_b128 v[216:219], v245 offset:32
	ds_read_b128 v[220:223], v245 offset:64
	ds_read_b128 v[224:227], v245 offset:96
	s_waitcnt lgkmcnt(0)
	v_rcp_f32_e32 v212, v212
	v_rcp_f32_e32 v213, v213
	v_rcp_f32_e32 v214, v214
	v_rcp_f32_e32 v215, v215
	v_rcp_f32_e32 v216, v216
	v_rcp_f32_e32 v217, v217
	v_rcp_f32_e32 v218, v218
	v_rcp_f32_e32 v219, v219
	v_rcp_f32_e32 v220, v220
	v_rcp_f32_e32 v221, v221
	v_rcp_f32_e32 v222, v222
	v_rcp_f32_e32 v223, v223
	v_rcp_f32_e32 v224, v224
	v_rcp_f32_e32 v225, v225
	v_rcp_f32_e32 v226, v226
	v_rcp_f32_e32 v227, v227
	v_add_u32_e32 v246, 0x0, v202
	v_mul_f32_e32 v0, v0, v212
	v_bfe_u32 v247, v0, 16, 1
	v_add3_u32 v0, v0, v247, s33
	global_store_short_d16_hi v246, v0, s[42:43] offset:0
	v_mul_f32_e32 v16, v16, v212
	v_bfe_u32 v247, v16, 16, 1
	v_add3_u32 v16, v16, v247, s33
	global_store_short_d16_hi v246, v16, s[42:43] offset:64
	v_mul_f32_e32 v1, v1, v213
	v_bfe_u32 v247, v1, 16, 1
	v_add3_u32 v1, v1, v247, s33
	global_store_short_d16_hi v246, v1, s[42:43] offset:2048
	v_mul_f32_e32 v17, v17, v213
	v_bfe_u32 v247, v17, 16, 1
	v_add3_u32 v17, v17, v247, s33
	global_store_short_d16_hi v246, v17, s[42:43] offset:2112
	v_add_u32_e32 v246, 0x1000, v202
	v_mul_f32_e32 v2, v2, v214
	v_bfe_u32 v247, v2, 16, 1
	v_add3_u32 v2, v2, v247, s33
	global_store_short_d16_hi v246, v2, s[42:43] offset:0
	v_mul_f32_e32 v18, v18, v214
	v_bfe_u32 v247, v18, 16, 1
	v_add3_u32 v18, v18, v247, s33
	global_store_short_d16_hi v246, v18, s[42:43] offset:64
	v_mul_f32_e32 v3, v3, v215
	v_bfe_u32 v247, v3, 16, 1
	v_add3_u32 v3, v3, v247, s33
	global_store_short_d16_hi v246, v3, s[42:43] offset:2048
	v_mul_f32_e32 v19, v19, v215
	v_bfe_u32 v247, v19, 16, 1
	v_add3_u32 v19, v19, v247, s33
	global_store_short_d16_hi v246, v19, s[42:43] offset:2112
	v_add_u32_e32 v246, 0x4000, v202
	v_mul_f32_e32 v4, v4, v216
	v_bfe_u32 v247, v4, 16, 1
	v_add3_u32 v4, v4, v247, s33
	global_store_short_d16_hi v246, v4, s[42:43] offset:0
	v_mul_f32_e32 v20, v20, v216
	v_bfe_u32 v247, v20, 16, 1
	v_add3_u32 v20, v20, v247, s33
	global_store_short_d16_hi v246, v20, s[42:43] offset:64
	v_mul_f32_e32 v5, v5, v217
	v_bfe_u32 v247, v5, 16, 1
	v_add3_u32 v5, v5, v247, s33
	global_store_short_d16_hi v246, v5, s[42:43] offset:2048
	v_mul_f32_e32 v21, v21, v217
	v_bfe_u32 v247, v21, 16, 1
	v_add3_u32 v21, v21, v247, s33
	global_store_short_d16_hi v246, v21, s[42:43] offset:2112
	v_add_u32_e32 v246, 0x5000, v202
	v_mul_f32_e32 v6, v6, v218
	v_bfe_u32 v247, v6, 16, 1
	v_add3_u32 v6, v6, v247, s33
	global_store_short_d16_hi v246, v6, s[42:43] offset:0
	v_mul_f32_e32 v22, v22, v218
	v_bfe_u32 v247, v22, 16, 1
	v_add3_u32 v22, v22, v247, s33
	global_store_short_d16_hi v246, v22, s[42:43] offset:64
	v_mul_f32_e32 v7, v7, v219
	v_bfe_u32 v247, v7, 16, 1
	v_add3_u32 v7, v7, v247, s33
	global_store_short_d16_hi v246, v7, s[42:43] offset:2048
	v_mul_f32_e32 v23, v23, v219
	v_bfe_u32 v247, v23, 16, 1
	v_add3_u32 v23, v23, v247, s33
	global_store_short_d16_hi v246, v23, s[42:43] offset:2112
	v_add_u32_e32 v246, 0x8000, v202
	v_mul_f32_e32 v8, v8, v220
	v_bfe_u32 v247, v8, 16, 1
	v_add3_u32 v8, v8, v247, s33
	global_store_short_d16_hi v246, v8, s[42:43] offset:0
	v_mul_f32_e32 v24, v24, v220
	v_bfe_u32 v247, v24, 16, 1
	v_add3_u32 v24, v24, v247, s33
	global_store_short_d16_hi v246, v24, s[42:43] offset:64
	v_mul_f32_e32 v9, v9, v221
	v_bfe_u32 v247, v9, 16, 1
	v_add3_u32 v9, v9, v247, s33
; __device__ __forceinline__ unsigned f2bf(float f) { unsigned u = __builtin_bit_cast(unsigned, f); return (u + 0x7fffu + ((u >> 16) & 1u)) >> 16; }
; __device__ __forceinline__ int crow(int r, int hi) { return (r & 3) + 8 * (r >> 2) + 4 * hi; }
; __device__ __forceinline__ void attn_body(const bf16_t* __restrict__ Qb, const bf16_t* __restrict__ KVh, const bf16_t* __restrict__ KR, const float* __restrict__ ropeq,
;                                           bf16_t* __restrict__ Ob, int seq, char* lds, const int tid) {
;     ...
;     if (hi == 0) li_l[r32] = l_reg; asm volatile("s_waitcnt lgkmcnt(0)" ::: "memory");
;     float rli[16];
; #pragma unroll
;     for (int r = 0; r < 16; ++r) rli[r] = __builtin_amdgcn_rcpf(li_l[crow(r, hi)]);
;     bf16_t* Ow = Ob + (size_t)(wid * QBLK) * DM;
; #pragma unroll
;     for (int r = 0; r < 16; ++r) { const int orow = crow(r, hi);
; #pragma unroll
;         for (int d0 = 0; d0 < 2; ++d0) Ow[(size_t)orow * DM + d0 * 32 + r32] = (bf16_t)f2bf(o[d0][r] * rli[r]); }
	global_store_short_d16_hi v246, v9, s[42:43] offset:2048
	v_mul_f32_e32 v25, v25, v221
	v_bfe_u32 v247, v25, 16, 1
	v_add3_u32 v25, v25, v247, s33
	global_store_short_d16_hi v246, v25, s[42:43] offset:2112
	v_add_u32_e32 v246, 0x9000, v202
	v_mul_f32_e32 v10, v10, v222
	v_bfe_u32 v247, v10, 16, 1
	v_add3_u32 v10, v10, v247, s33
	global_store_short_d16_hi v246, v10, s[42:43] offset:0
	v_mul_f32_e32 v26, v26, v222
	v_bfe_u32 v247, v26, 16, 1
	v_add3_u32 v26, v26, v247, s33
	global_store_short_d16_hi v246, v26, s[42:43] offset:64
	v_mul_f32_e32 v11, v11, v223
	v_bfe_u32 v247, v11, 16, 1
	v_add3_u32 v11, v11, v247, s33
	global_store_short_d16_hi v246, v11, s[42:43] offset:2048
	v_mul_f32_e32 v27, v27, v223
	v_bfe_u32 v247, v27, 16, 1
	v_add3_u32 v27, v27, v247, s33
	global_store_short_d16_hi v246, v27, s[42:43] offset:2112
	v_add_u32_e32 v246, 0xc000, v202
	v_mul_f32_e32 v12, v12, v224
	v_bfe_u32 v247, v12, 16, 1
	v_add3_u32 v12, v12, v247, s33
	global_store_short_d16_hi v246, v12, s[42:43] offset:0
	v_mul_f32_e32 v28, v28, v224
	v_bfe_u32 v247, v28, 16, 1
	v_add3_u32 v28, v28, v247, s33
	global_store_short_d16_hi v246, v28, s[42:43] offset:64
	v_mul_f32_e32 v13, v13, v225
	v_bfe_u32 v247, v13, 16, 1
	v_add3_u32 v13, v13, v247, s33
	global_store_short_d16_hi v246, v13, s[42:43] offset:2048
	v_mul_f32_e32 v29, v29, v225
	v_bfe_u32 v247, v29, 16, 1
	v_add3_u32 v29, v29, v247, s33
	global_store_short_d16_hi v246, v29, s[42:43] offset:2112
	v_add_u32_e32 v246, 0xd000, v202
	v_mul_f32_e32 v14, v14, v226
	v_bfe_u32 v247, v14, 16, 1
	v_add3_u32 v14, v14, v247, s33
	global_store_short_d16_hi v246, v14, s[42:43] offset:0
	v_mul_f32_e32 v30, v30, v226
	v_bfe_u32 v247, v30, 16, 1
	v_add3_u32 v30, v30, v247, s33
	global_store_short_d16_hi v246, v30, s[42:43] offset:64
	v_mul_f32_e32 v15, v15, v227
	v_bfe_u32 v247, v15, 16, 1
	v_add3_u32 v15, v15, v247, s33
	global_store_short_d16_hi v246, v15, s[42:43] offset:2048
	v_mul_f32_e32 v31, v31, v227
	v_bfe_u32 v247, v31, 16, 1
	v_add3_u32 v31, v31, v247, s33
	global_store_short_d16_hi v246, v31, s[42:43] offset:2112
	s_waitcnt lgkmcnt(0)
	v_mov_b32_e32 v203, v255
	s_nop 1
	v_permlane32_swap_b32_e32 v255, v203
	v_add_f32_e32 v255, v255, v203
	s_and_saveexec_b64 s[60:61], s[4:5]
	ds_write_b32 v234, v255
	s_or_b64 exec, exec, s[60:61]
	s_waitcnt lgkmcnt(0)
	v_add_u32_e32 v245, v232, v233
	ds_read_b128 v[212:215], v245 offset:0
	ds_read_b128 v[216:219], v245 offset:32
	ds_read_b128 v[220:223], v245 offset:64
	ds_read_b128 v[224:227], v245 offset:96
	s_waitcnt lgkmcnt(0)
; __device__ __forceinline__ unsigned f2bf(float f) { unsigned u = __builtin_bit_cast(unsigned, f); return (u + 0x7fffu + ((u >> 16) & 1u)) >> 16; }
; __device__ __forceinline__ int crow(int r, int hi) { return (r & 3) + 8 * (r >> 2) + 4 * hi; }
; __device__ __forceinline__ void attn_body(const bf16_t* __restrict__ Qb, const bf16_t* __restrict__ KVh, const bf16_t* __restrict__ KR, const float* __restrict__ ropeq,
;                                           bf16_t* __restrict__ Ob, int seq, char* lds, const int tid) {
;     ...
;     if (hi == 0) li_l[r32] = l_reg; asm volatile("s_waitcnt lgkmcnt(0)" ::: "memory");
;     float rli[16];
; #pragma unroll
;     for (int r = 0; r < 16; ++r) rli[r] = __builtin_amdgcn_rcpf(li_l[crow(r, hi)]);
;     bf16_t* Ow = Ob + (size_t)(wid * QBLK) * DM;
; #pragma unroll
;     for (int r = 0; r < 16; ++r) { const int orow = crow(r, hi);
; #pragma unroll
;         for (int d0 = 0; d0 < 2; ++d0) Ow[(size_t)orow * DM + d0 * 32 + r32] = (bf16_t)f2bf(o[d0][r] * rli[r]); }
; __device__ __forceinline__ void phase_attn(const Ctx& C, PP p, char* lds_generic) {
;     ...
;     for (int it = C.vcu; it < 2048; it += C.G) {
;         const int qb = it & 15, h = (it >> 4) & 15, b = it >> 8; const size_t t0 = (size_t)b * SEQ, q0 = t0 + qb * 256;
;         __syncthreads();
;         att::attn_body(Q + q0 * NQ + h * 96, KV + t0 * NKV + h * 128, KR + t0 * 32, rope + q0 * 32, O + q0 * DM + h * 64, SEQ, lds_generic, C.tid);
;     }
	v_rcp_f32_e32 v212, v212
	v_rcp_f32_e32 v213, v213
	v_rcp_f32_e32 v214, v214
	v_rcp_f32_e32 v215, v215
	v_rcp_f32_e32 v216, v216
	v_rcp_f32_e32 v217, v217
	v_rcp_f32_e32 v218, v218
	v_rcp_f32_e32 v219, v219
	v_rcp_f32_e32 v220, v220
	v_rcp_f32_e32 v221, v221
	v_rcp_f32_e32 v222, v222
	v_rcp_f32_e32 v223, v223
	v_rcp_f32_e32 v224, v224
	v_rcp_f32_e32 v225, v225
	v_rcp_f32_e32 v226, v226
	v_rcp_f32_e32 v227, v227
	v_add_u32_e32 v246, 0x10000, v202
	v_mul_f32_e32 v32, v32, v212
	v_bfe_u32 v247, v32, 16, 1
	v_add3_u32 v32, v32, v247, s33
	global_store_short_d16_hi v246, v32, s[42:43] offset:0
	v_mul_f32_e32 v48, v48, v212
	v_bfe_u32 v247, v48, 16, 1
	v_add3_u32 v48, v48, v247, s33
	global_store_short_d16_hi v246, v48, s[42:43] offset:64
	v_mul_f32_e32 v33, v33, v213
	v_bfe_u32 v247, v33, 16, 1
	v_add3_u32 v33, v33, v247, s33
	global_store_short_d16_hi v246, v33, s[42:43] offset:2048
	v_mul_f32_e32 v49, v49, v213
	v_bfe_u32 v247, v49, 16, 1
	v_add3_u32 v49, v49, v247, s33
	global_store_short_d16_hi v246, v49, s[42:43] offset:2112
	v_add_u32_e32 v246, 0x11000, v202
	v_mul_f32_e32 v34, v34, v214
	v_bfe_u32 v247, v34, 16, 1
	v_add3_u32 v34, v34, v247, s33
	global_store_short_d16_hi v246, v34, s[42:43] offset:0
	v_mul_f32_e32 v50, v50, v214
	v_bfe_u32 v247, v50, 16, 1
	v_add3_u32 v50, v50, v247, s33
	global_store_short_d16_hi v246, v50, s[42:43] offset:64
	v_mul_f32_e32 v35, v35, v215
	v_bfe_u32 v247, v35, 16, 1
	v_add3_u32 v35, v35, v247, s33
	global_store_short_d16_hi v246, v35, s[42:43] offset:2048
	v_mul_f32_e32 v51, v51, v215
	v_bfe_u32 v247, v51, 16, 1
	v_add3_u32 v51, v51, v247, s33
	global_store_short_d16_hi v246, v51, s[42:43] offset:2112
	v_add_u32_e32 v246, 0x14000, v202
	v_mul_f32_e32 v36, v36, v216
	v_bfe_u32 v247, v36, 16, 1
	v_add3_u32 v36, v36, v247, s33
	global_store_short_d16_hi v246, v36, s[42:43] offset:0
	v_mul_f32_e32 v52, v52, v216
	v_bfe_u32 v247, v52, 16, 1
	v_add3_u32 v52, v52, v247, s33
	global_store_short_d16_hi v246, v52, s[42:43] offset:64
	v_mul_f32_e32 v37, v37, v217
	v_bfe_u32 v247, v37, 16, 1
	v_add3_u32 v37, v37, v247, s33
	global_store_short_d16_hi v246, v37, s[42:43] offset:2048
	v_mul_f32_e32 v53, v53, v217
	v_bfe_u32 v247, v53, 16, 1
	v_add3_u32 v53, v53, v247, s33
	global_store_short_d16_hi v246, v53, s[42:43] offset:2112
	v_add_u32_e32 v246, 0x15000, v202
	v_mul_f32_e32 v38, v38, v218
	v_bfe_u32 v247, v38, 16, 1
	v_add3_u32 v38, v38, v247, s33
	global_store_short_d16_hi v246, v38, s[42:43] offset:0
	v_mul_f32_e32 v54, v54, v218
	v_bfe_u32 v247, v54, 16, 1
	v_add3_u32 v54, v54, v247, s33
	global_store_short_d16_hi v246, v54, s[42:43] offset:64
	v_mul_f32_e32 v39, v39, v219
	v_bfe_u32 v247, v39, 16, 1
	v_add3_u32 v39, v39, v247, s33
	global_store_short_d16_hi v246, v39, s[42:43] offset:2048
	v_mul_f32_e32 v55, v55, v219
	v_bfe_u32 v247, v55, 16, 1
	v_add3_u32 v55, v55, v247, s33
	global_store_short_d16_hi v246, v55, s[42:43] offset:2112
	v_add_u32_e32 v246, 0x18000, v202
	v_mul_f32_e32 v40, v40, v220
	v_bfe_u32 v247, v40, 16, 1
	v_add3_u32 v40, v40, v247, s33
	global_store_short_d16_hi v246, v40, s[42:43] offset:0
	v_mul_f32_e32 v56, v56, v220
	v_bfe_u32 v247, v56, 16, 1
	v_add3_u32 v56, v56, v247, s33
	global_store_short_d16_hi v246, v56, s[42:43] offset:64
	v_mul_f32_e32 v41, v41, v221
	v_bfe_u32 v247, v41, 16, 1
	v_add3_u32 v41, v41, v247, s33
	global_store_short_d16_hi v246, v41, s[42:43] offset:2048
	v_mul_f32_e32 v57, v57, v221
	v_bfe_u32 v247, v57, 16, 1
	v_add3_u32 v57, v57, v247, s33
	global_store_short_d16_hi v246, v57, s[42:43] offset:2112
	v_add_u32_e32 v246, 0x19000, v202
	v_mul_f32_e32 v42, v42, v222
	v_bfe_u32 v247, v42, 16, 1
	v_add3_u32 v42, v42, v247, s33
	global_store_short_d16_hi v246, v42, s[42:43] offset:0
	v_mul_f32_e32 v58, v58, v222
	v_bfe_u32 v247, v58, 16, 1
	v_add3_u32 v58, v58, v247, s33
	global_store_short_d16_hi v246, v58, s[42:43] offset:64
	v_mul_f32_e32 v43, v43, v223
	v_bfe_u32 v247, v43, 16, 1
	v_add3_u32 v43, v43, v247, s33
	global_store_short_d16_hi v246, v43, s[42:43] offset:2048
	v_mul_f32_e32 v59, v59, v223
	v_bfe_u32 v247, v59, 16, 1
	v_add3_u32 v59, v59, v247, s33
	global_store_short_d16_hi v246, v59, s[42:43] offset:2112
	v_add_u32_e32 v246, 0x1c000, v202
	v_mul_f32_e32 v44, v44, v224
	v_bfe_u32 v247, v44, 16, 1
	v_add3_u32 v44, v44, v247, s33
	global_store_short_d16_hi v246, v44, s[42:43] offset:0
	v_mul_f32_e32 v60, v60, v224
	v_bfe_u32 v247, v60, 16, 1
	v_add3_u32 v60, v60, v247, s33
	global_store_short_d16_hi v246, v60, s[42:43] offset:64
	v_mul_f32_e32 v45, v45, v225
	v_bfe_u32 v247, v45, 16, 1
	v_add3_u32 v45, v45, v247, s33
	global_store_short_d16_hi v246, v45, s[42:43] offset:2048
	v_mul_f32_e32 v61, v61, v225
	v_bfe_u32 v247, v61, 16, 1
	v_add3_u32 v61, v61, v247, s33
	global_store_short_d16_hi v246, v61, s[42:43] offset:2112
	v_add_u32_e32 v246, 0x1d000, v202
	v_mul_f32_e32 v46, v46, v226
	v_bfe_u32 v247, v46, 16, 1
	v_add3_u32 v46, v46, v247, s33
	global_store_short_d16_hi v246, v46, s[42:43] offset:0
	v_mul_f32_e32 v62, v62, v226
	v_bfe_u32 v247, v62, 16, 1
	v_add3_u32 v62, v62, v247, s33
	global_store_short_d16_hi v246, v62, s[42:43] offset:64
	v_mul_f32_e32 v47, v47, v227
	v_bfe_u32 v247, v47, 16, 1
	v_add3_u32 v47, v47, v247, s33
	global_store_short_d16_hi v246, v47, s[42:43] offset:2048
	v_mul_f32_e32 v63, v63, v227
	v_bfe_u32 v247, v63, 16, 1
	v_add3_u32 v63, v63, v247, s33
	global_store_short_d16_hi v246, v63, s[42:43] offset:2112
	s_waitcnt lgkmcnt(0)
	s_add_i32 s20, s20, s85
	s_cmpk_lt_i32 s20, 0x400
	s_cbranch_scc1 .LA_item
	s_branch .LBB0_78
